# P1-P2, P5-P6, P6-P7 grid barriers XCD-local when all workgroups of each blockIdx&7 group report the same XCC_ID (runtime check via atomic umax/umin words; full barrier otherwise)
# speedup vs baseline: 1.0045x; 1.0034x over previous
; #define LAS __attribute__((address_space(3)))
; __device__ __forceinline__ unsigned xb_add(unsigned* p, unsigned v) { return __hip_atomic_fetch_add(p, v, __ATOMIC_RELAXED, __HIP_MEMORY_SCOPE_AGENT); }
; __device__ __forceinline__ unsigned xb_xcc_id() { return (unsigned)__builtin_amdgcn_s_getreg((3 << 11) | 20) & 0xFu; }
; __device__ __forceinline__ XcdBarrier xcd_barrier_post(unsigned* bar, volatile LAS unsigned* st) {
;     XcdBarrier b; b.bar = bar; b.x = xb_xcc_id(); b.st = st;
;     if (threadIdx.x == 0) (void)xb_add(&bar[XB_XCNT(b.x)], 1u);
;     return b;
; }
.LBB0_14:
	s_add_u32 s2, s10, 0x80000
	s_addc_u32 s3, s11, 0
	v_writelane_b32 v235, s2, 8
	v_cmp_eq_u32_e64 s[4:5], 0, v189
	s_nop 0
	v_writelane_b32 v235, s3, 9
	s_getreg_b32 s2, hwreg(HW_REG_XCC_ID, 0, 4)
	s_and_b32 s2, s2, 15
	v_writelane_b32 v235, s2, 10
	s_mov_b64 s[2:3], exec
	v_writelane_b32 v235, s4, 11
	s_nop 1
	v_writelane_b32 v235, s5, 12
	s_and_b64 s[4:5], s[2:3], s[4:5]
	s_mov_b64 exec, s[4:5]
	s_cbranch_execz .LBB0_17
	s_mov_b64 s[4:5], exec
	v_mbcnt_lo_u32_b32 v0, s4, 0
	v_mbcnt_hi_u32_b32 v0, s5, v0
	v_cmp_eq_u32_e32 vcc, 0, v0
	s_and_b64 s[6:7], exec, vcc
	s_mov_b64 exec, s[6:7]
	s_cbranch_execz .LBB0_17
	v_readlane_b32 s6, v235, 10
	s_bcnt1_i32_b64 s4, s[4:5]
	s_lshl_b32 s6, s6, 8
	v_mov_b32_e32 v1, s4
	v_readlane_b32 s4, v235, 8
	v_mov_b32_e32 v0, s6
	v_readlane_b32 s5, v235, 9
	s_nop 4
	global_atomic_add v0, v1, s[4:5] offset:1024
	v_readlane_b32 s6, v235, 10
	v_readlane_b32 s7, v235, 0
	s_nop 0
	s_and_b32 s7, s7, 7
	s_lshl_b32 s7, s7, 3
	s_add_u32 s7, s7, 0x3800
	v_mov_b32_e32 v0, s7
	s_add_u32 s7, s6, 1
	v_mov_b32_e32 v1, s7
	global_atomic_umax v0, v1, s[4:5]
	s_sub_u32 s7, 16, s6
	v_mov_b32_e32 v1, s7
	global_atomic_umax v0, v1, s[4:5] offset:4

; #define PG8_WAIT_V(n) asm volatile("s_waitcnt vmcnt(" #n ")" ::: "memory")
; #define PG8_BAR __builtin_amdgcn_s_barrier()
; template <class Epi, class Sched, bool ALIGN_EPI = false, bool SP2 = false>
; __device__ __forceinline__ void gemm_phase(PG8_LAS unsigned char* lds, const Gemm g, const Sched& S, const Epi& E) {
;     ...
;     const int wid = __builtin_amdgcn_readfirstlane(tid >> 6), lane = tid & 63, wr = wid >> 2, wc = wid & 3, fr = lane & 15, fq = lane >> 4;
;     const int K = g.K, nt = K / BK;
;     unsigned voffA[2], voffB[2];
; #pragma unroll
;     for (int i = 0; i < 2; ++i) { int R, C; stage_rc(tid * 16 + i * 8192, R, C); const int Rb = Epi::PERM ? ((R & ~31) + perm32(R & 31)) : R;
;         voffA[i] = (unsigned)(R * K + C) * 2u; voffB[i] = (unsigned)(Rb * K + C) * 2u; }
;     const size_t kstep = (size_t)(BK * 2);
;     const size_t hstep = (size_t)HALF * K * 2;
;     const size_t tstep = 2 * hstep;
;     const unsigned ldsw = (unsigned)wid * 1024u;
;     const int aoff = lds_byte(wr * 64 + fr, fq * 8), boff = lds_byte(wc * 32 + fr, fq * 8);
;     ...
;     Unit cur, nxt; int ui = 0;
;     if (!S.next(0, cur)) return;
;     f32x4 acc[2][2][4][2];
; #pragma unroll
;     for (int a = 0; a < 2; ++a)
; #pragma unroll
;         for (int b = 0; b < 2; ++b)
; #pragma unroll
;             for (int m = 0; m < 4; ++m)
; #pragma unroll
;                 for (int n = 0; n < 2; ++n) acc[a][b][m][n] = (f32x4){0.f, 0.f, 0.f, 0.f};
;     bf16x8 At[4][2], B0[2][2], B1[2][2];
;     const char* cA = (const char*)g.A + (size_t)cur.pm * tstep; const char* cB = (const char*)g.Bt + (size_t)cur.pn * tstep;
;     S.a_ready(cur);
;     if constexpr (SP2) {
;         PG8_STAGE(PG8_SB(0, 0), cB, voffB); PG8_STAGE(PG8_SB(0, 1), cB + hstep, voffB); PG8_STAGE(PG8_SA(0, 0), cA, voffA); PG8_STAGE(PG8_SA(0, 1), cA + hstep, voffA);
;         if (wr == 1) PG8_BAR;
;         PG8_WAIT_V(2); PG8_BAR;
;         PG8_STAGE(PG8_SB(1, 0), cB + kstep, voffB); PG8_STAGE(PG8_SA(1, 0), cA + kstep, voffA); PG8_STAGE(PG8_SB(1, 1), cB + hstep + kstep, voffB);
;         PG8_WAIT_V(6); PG8_BAR;
;     } else {
;         PG8_STAGE(PG8_SB(0, 0), cB, voffB); PG8_STAGE(PG8_SA(0, 0), cA, voffA); PG8_STAGE(PG8_SB(0, 1), cB + hstep, voffB); PG8_STAGE(PG8_SA(0, 1), cA + hstep, voffA);
;         if (wr == 1) PG8_BAR;
;         PG8_WAIT_V(4); PG8_BAR;
.LBB0_183:
	s_or_b64 exec, exec, s[0:1]
	v_readlane_b32 s4, v235, 8
	v_readlane_b32 s5, v235, 9
	v_and_b32_e32 v0, 7, v189
	v_lshlrev_b32_e32 v0, 3, v0
	v_add_u32_e32 v0, 0x3800, v0
	s_nop 1
	global_load_dwordx2 v[0:1], v0, s[4:5] sc1
	s_waitcnt vmcnt(0)
	v_add_u32_e32 v0, v0, v1
	v_cmp_ne_u32_e32 vcc, 17, v0
	s_cmp_lg_u64 vcc, 0
	s_cselect_b32 s4, 1, 0
	v_mov_b32_e32 v0, 0x20170
	v_mov_b32_e32 v1, s4
	ds_write_b32 v0, v1
	v_readlane_b32 s0, v235, 2
	v_readlane_b32 s2, v235, 4
	v_readlane_b32 s1, v235, 3
	v_readlane_b32 s3, v235, 5
	s_add_u32 s0, s2, 0x7000000
	s_addc_u32 s1, s3, 0
	v_writelane_b32 v235, s0, 33
	v_mov_b32_e32 v9, v189
	s_waitcnt lgkmcnt(0)
	v_writelane_b32 v235, s1, 34
	s_barrier
	v_readlane_b32 s0, v235, 0
	s_cmpk_lt_i32 s0, 0xb00
	s_cselect_b64 s[2:3], -1, 0
	v_writelane_b32 v235, s2, 35
	s_cmpk_gt_i32 s0, 0xaff
	v_readfirstlane_b32 s1, v9
	v_writelane_b32 v235, s3, 36
	s_cbranch_scc1 .LBB0_199
	v_lshlrev_b32_e32 v0, 4, v9
	v_add_u32_e32 v1, 0x2000, v0
	v_ashrrev_i32_e32 v2, 31, v1
	v_lshrrev_b32_e32 v2, 22, v2
	v_add_u32_e32 v2, v1, v2
	v_ashrrev_i32_e32 v8, 10, v2
	v_mul_i32_i24_e32 v2, 0x400, v8
	v_sub_u32_e32 v1, v1, v2
	v_lshrrev_b32_e32 v2, 4, v1
	v_bitop3_b32 v1, v2, v1, 32 bitop3:0x6c
	v_ashrrev_i32_e32 v2, 31, v1
	v_lshrrev_b32_e32 v2, 26, v2
	v_add_u32_e32 v2, v1, v2
	v_lshlrev_b32_e32 v3, 3, v8
	v_ashrrev_i32_e32 v10, 6, v2
	v_and_b32_e32 v3, -16, v3
	v_add_u32_e32 v3, v10, v3
	v_and_b32_e32 v4, 3, v10
	s_mov_b32 s0, 0x1fffe0
	v_lshrrev_b32_e32 v5, 2, v3
	v_lshlrev_b32_e32 v6, 1, v3
	v_and_b32_e32 v2, 0xc0, v2
	v_and_or_b32 v4, v3, s0, v4
	v_and_b32_e32 v5, 4, v5
	v_and_b32_e32 v6, 24, v6
	v_sub_u32_e32 v1, v1, v2
	v_mov_b32_e32 v2, 1
	v_or3_b32 v4, v4, v5, v6
	v_lshlrev_b32_e32 v5, 5, v8
	v_ashrrev_i16_sdwa v1, v2, sext(v1) dst_sel:DWORD dst_unused:UNUSED_PAD src0_sel:DWORD src1_sel:BYTE_0
	v_and_b32_e32 v5, 32, v5
	v_bfe_i32 v11, v1, 0, 16
	v_add_lshl_u32 v1, v5, v11, 1
	v_lshl_add_u32 v128, v4, 11, v1
	v_lshl_add_u32 v130, v3, 11, v1
	v_bfe_i32 v1, v9, 27, 1
	v_lshrrev_b32_e32 v1, 22, v1
	v_add_u32_e32 v1, v0, v1
	v_and_b32_e32 v1, 0xfffffc00, v1
	v_sub_u32_e32 v0, v0, v1
	v_lshrrev_b32_e32 v1, 4, v0
	v_ashrrev_i32_e32 v3, 31, v9
	v_bitop3_b32 v0, v1, v0, 32 bitop3:0x6c
	v_lshrrev_b32_e32 v3, 26, v3
	v_ashrrev_i32_e32 v1, 31, v0
	v_add_u32_e32 v3, v9, v3
	v_readlane_b32 s4, v235, 2
	v_lshrrev_b32_e32 v1, 26, v1
	v_ashrrev_i32_e32 v13, 6, v3
	v_readlane_b32 s6, v235, 4
	v_add_u32_e32 v1, v0, v1
	v_lshlrev_b32_e32 v3, 3, v13
	v_readlane_b32 s7, v235, 5
	s_add_u32 s33, s6, 0x200000
	v_ashrrev_i32_e32 v12, 6, v1
	v_and_b32_e32 v3, -16, v3
	v_readlane_b32 s3, v235, 0
	s_addc_u32 s34, s7, 0
	v_add_u32_e32 v3, v12, v3
	v_and_b32_e32 v4, 3, v12
	s_ashr_i32 s36, s3, 31
	v_and_or_b32 v4, v3, s0, v4
	s_lshr_b32 s0, s36, 29
	s_add_i32 s0, s3, s0
	s_ashr_i32 s4, s1, 6
	s_ashr_i32 s2, s0, 3
	s_and_b32 s0, s0, -8
	s_ashr_i32 s6, s1, 8
	s_lshl_b32 s35, s4, 10
	s_sub_i32 s0, s3, s0
	s_cmp_lt_i32 s0, 0
	s_movk_i32 s37, 0x161
	s_cselect_b32 s3, s37, 0x160
	s_mul_i32 s0, s0, s3
	s_add_i32 s0, s0, s2
	s_mul_hi_i32 s2, s0, 0x2e8ba2e9
	s_lshr_b32 s3, s2, 31
	s_ashr_i32 s2, s2, 4
	s_add_i32 s2, s2, s3
	s_lshl_b32 s3, s2, 2
	s_mulk_i32 s2, 0x58
	s_sub_i32 s2, s0, s2
	s_bfe_i32 s0, s2, 0x80000
	v_readlane_b32 s5, v235, 3
	s_bfe_u32 s0, s0, 0x2000d
	s_add_i32 s5, s2, s0
	s_bfe_i32 s0, s5, 0x80000
	s_and_b32 s5, s5, 0xfc
	s_sub_i32 s2, s2, s5
	s_sext_i32_i16 s0, s0
	s_sext_i32_i8 s2, s2
	v_lshrrev_b32_e32 v5, 2, v3
	v_lshlrev_b32_e32 v6, 1, v3
	v_and_b32_e32 v1, 0xc0, v1
	s_lshr_b32 s0, s0, 2
	s_add_i32 s20, s3, s2
	v_and_b32_e32 v5, 4, v5
	v_and_b32_e32 v6, 24, v6
	v_sub_u32_e32 v0, v0, v1
	s_ashr_i32 s21, s20, 31
	s_bfe_i64 s[8:9], s[0:1], 0x100000
	v_or3_b32 v4, v4, v5, v6
	v_lshlrev_b32_e32 v5, 5, v13
	v_ashrrev_i16_sdwa v0, v2, sext(v0) dst_sel:DWORD dst_unused:UNUSED_PAD src0_sel:DWORD src1_sel:BYTE_0
	s_lshl_b64 s[2:3], s[20:21], 19
	s_lshl_b64 s[8:9], s[8:9], 19
	v_and_b32_e32 v5, 32, v5
	v_bfe_i32 v14, v0, 0, 16
	s_add_u32 s24, s33, s8
	v_add_lshl_u32 v0, v5, v14, 1
	s_addc_u32 s25, s34, s9
	s_add_i32 s21, s35, 0
	v_lshl_add_u32 v132, v4, 11, v0
	s_add_i32 m0, s21, 0x10000
	v_lshl_add_u32 v134, v3, 11, v0
	global_load_lds_dwordx4 v132, s[24:25]
	s_add_i32 m0, s21, 0x12000
	s_add_u32 s8, s24, 0x40000
	global_load_lds_dwordx4 v128, s[24:25]
	s_addc_u32 s9, s25, 0
	s_add_i32 m0, s21, 0x14000
	v_mov_b32_e32 v133, 0
	global_load_lds_dwordx4 v132, s[8:9]
	s_add_i32 m0, s21, 0x16000
	v_mov_b32_e32 v129, v133
	global_load_lds_dwordx4 v128, s[8:9]
	v_readlane_b32 s8, v235, 31
	v_readlane_b32 s9, v235, 32
	s_add_u32 s22, s8, s2
	s_addc_u32 s23, s9, s3
	s_add_i32 s38, s21, 0x2000
	s_mov_b32 m0, s21
	s_add_u32 s2, s22, 0x40000
	global_load_lds_dwordx4 v134, s[22:23]
	s_mov_b32 m0, s38
	s_addc_u32 s3, s23, 0
	s_add_i32 s39, s21, 0x4000
	global_load_lds_dwordx4 v130, s[22:23]
	s_mov_b32 m0, s39
	s_add_i32 s40, s21, 0x6000
	global_load_lds_dwordx4 v134, s[2:3]
	s_mov_b32 m0, s40
	v_mov_b32_e32 v135, v133
	global_load_lds_dwordx4 v130, s[2:3]
	v_mov_b32_e32 v131, v133
	s_cmp_eq_u32 s6, 1
	s_mov_b32 s41, 0
	v_lshl_add_u64 v[6:7], s[24:25], 0, v[132:133]
	v_lshl_add_u64 v[4:5], s[24:25], 0, v[128:129]
	v_lshl_add_u64 v[0:1], s[22:23], 0, v[134:135]
	s_cselect_b64 s[2:3], -1, 0
	s_cmp_lg_u32 s6, 1
	v_lshl_add_u64 v[2:3], s[22:23], 0, v[130:131]
	s_cbranch_scc1 .LBB0_186
	s_barrier
